# code placement: branch-merge GEMM K-loop also at 0 mod 8 (all K-loops and attention tile loops now 8-byte aligned)
# baseline (speedup 1.0000x reference)
;     __device__ bool next(int i, Unit& u) const { u.aoff = 0; return tile((long)i * G + c, u.pm, u.pn); }
; template <class Epi, class Sched, bool ALIGN_EPI>
; __device__ __forceinline__ void gemm_phase(LAS unsigned char* lds, const Gemm g, const Sched& S, const Epi& E) {
;     ...
;     for (;;) {
;         const bool has_next = S.next(ui + 1, nxt);
;         const char* nA = has_next ? (const char*)g.A + (size_t)nxt.pm * tstepA + nxt.aoff : cA; const char* nB = has_next ? (const char*)g.Bt + (size_t)nxt.pn * tstepB : cB;
;         for (int t = 0; t < nt; t += 2) {
.LBB0_159:
	s_nop 0
	s_mov_b64 s[4:5], 0
